# grid barrier (6 in-loop sites): all waiters poll the top-level arrival counter until it reaches (generation+1)*nx; the generation words are no longer bumped, one atomic hop less on the release path
# speedup vs baseline: 1.0158x; 1.0044x over previous
.LBB0_421:
	s_or_b64 exec, exec, s[10:11]
	v_cvt_f32_u32_e32 v5, v3
	s_waitcnt vmcnt(0)
	v_readfirstlane_b32 s8, v4
	v_sub_u32_e32 v4, 0, v3
	v_rcp_iflag_f32_e32 v5, v5
	v_add_u32_e32 v6, s8, v0
	v_mul_f32_e32 v5, 0x4f7ffffe, v5
	v_cvt_u32_f32_e32 v5, v5
	v_mul_lo_u32 v0, v4, v5
	v_mul_hi_u32 v0, v5, v0
	v_add_u32_e32 v0, v5, v0
	v_mul_hi_u32 v0, v6, v0
	v_mul_lo_u32 v4, v0, v3
	v_sub_u32_e32 v4, v6, v4
	v_add_u32_e32 v5, 1, v0
	v_cmp_ge_u32_e32 vcc, v4, v3
	s_nop 1
	v_cndmask_b32_e32 v0, v0, v5, vcc
	v_sub_u32_e32 v5, v4, v3
	v_cndmask_b32_e32 v4, v4, v5, vcc
	v_add_u32_e32 v5, 1, v0
	v_cmp_ge_u32_e32 vcc, v4, v3
	v_add_u32_e32 v4, 1, v6
	s_nop 0
	v_cndmask_b32_e32 v0, v0, v5, vcc
	v_mul_lo_u32 v5, v3, v0
	v_add_u32_e32 v3, v5, v3
	v_cmp_ne_u32_e32 vcc, v4, v3
	s_and_saveexec_b64 s[8:9], vcc
	s_xor_b64 s[8:9], exec, s[8:9]
	s_cbranch_execz .LBB0_435
	s_waitcnt lgkmcnt(0)
	v_add_u32_e32 v5, 1, v0
	v_mul_lo_u32 v5, v5, v2
	v_readlane_b32 s12, v254, 15
	v_readlane_b32 s13, v254, 16
	s_nop 4
	global_load_dword v2, v1, s[12:13] sc1
	s_nop 0
	s_nop 0
	s_waitcnt vmcnt(0)
	v_cmp_lt_u32_e32 vcc, v2, v5
	s_and_saveexec_b64 s[10:11], vcc
	s_cbranch_execz .LBB0_434
	s_mov_b32 s22, 1
	s_mov_b64 s[14:15], 0
	s_branch .LBB0_425

.LBB0_427:
	global_load_dword v2, v1, s[12:13] sc1
	s_add_i32 s22, s22, 1
	s_mov_b64 s[38:39], -1
	s_waitcnt vmcnt(0)
	v_cmp_ge_u32_e32 vcc, v2, v5
	s_orn2_b64 s[26:27], vcc, exec
	s_branch .LBB0_424

.LBB0_438:
	s_or_b64 exec, exec, s[10:11]
	s_waitcnt vmcnt(0)
	v_readfirstlane_b32 s8, v3
	v_sub_u32_e32 v4, 0, v2
	s_mov_b64 s[10:11], 0
	v_add_u32_e32 v3, s8, v0
	v_cvt_f32_u32_e32 v0, v2
	v_readlane_b32 s8, v254, 17
	v_readlane_b32 s9, v254, 18
	v_rcp_iflag_f32_e32 v0, v0
	s_nop 0
	v_mul_f32_e32 v0, 0x4f7ffffe, v0
	v_cvt_u32_f32_e32 v0, v0
	v_mul_lo_u32 v4, v4, v0
	v_mul_hi_u32 v4, v0, v4
	v_add_u32_e32 v0, v0, v4
	v_mul_hi_u32 v0, v3, v0
	v_mul_lo_u32 v4, v0, v2
	v_sub_u32_e32 v4, v3, v4
	v_cmp_ge_u32_e32 vcc, v4, v2
	v_add_u32_e32 v5, 1, v0
	v_add_u32_e32 v3, 1, v3
	v_cndmask_b32_e32 v0, v0, v5, vcc
	v_sub_u32_e32 v5, v4, v2
	v_cndmask_b32_e32 v4, v4, v5, vcc
	v_cmp_ge_u32_e32 vcc, v4, v2
	v_add_u32_e32 v4, 1, v0
	s_nop 0
	v_cndmask_b32_e32 v0, v0, v4, vcc
	v_mul_lo_u32 v4, v2, v0
	v_add_u32_e32 v2, v4, v2
	v_cmp_ne_u32_e32 vcc, v3, v2
	v_mov_b32_e32 v5, v2
	v_mov_b64_e32 v[2:3], s[8:9]
	s_and_saveexec_b64 s[8:9], vcc
	s_cbranch_execz .LBB0_450
	v_readlane_b32 s10, v254, 15
	v_readlane_b32 s11, v254, 16
	s_mov_b64 s[12:13], 0
	s_nop 3
	global_load_dword v2, v1, s[10:11] sc1
	s_waitcnt vmcnt(0)
	v_cmp_lt_u32_e32 vcc, v2, v5
	s_and_saveexec_b64 s[10:11], vcc
	s_cbranch_execz .LBB0_449
	s_mov_b32 s22, 1
	s_branch .LBB0_442

.LBB0_444:
	v_readlane_b32 s16, v254, 15
	v_readlane_b32 s17, v254, 16
	s_add_i32 s22, s22, 1
	s_mov_b64 s[26:27], -1
	s_nop 2
	global_load_dword v2, v1, s[16:17] sc1
	s_waitcnt vmcnt(0)
	v_cmp_ge_u32_e32 vcc, v2, v5
	s_orn2_b64 s[16:17], vcc, exec
	s_branch .LBB0_441

.LBB0_602:
	global_load_dword v2, v1, s[12:13] sc1
	s_add_i32 s22, s22, 1
	s_mov_b64 s[36:37], -1
	s_waitcnt vmcnt(0)
	v_cmp_ge_u32_e32 vcc, v2, v5
	s_orn2_b64 s[26:27], vcc, exec
	s_branch .LBB0_599
